# write-through sc1 on the memKV GEMM epilogue stores (12 WGs on the layer-0 mixing critical path), on top of the permlane version
# baseline (speedup 1.0000x reference)
.LBB0_716:
	v_lshl_add_u32 v148, s35, 8, v1
	v_lshl_or_b32 v142, s21, 8, v151
	v_readlane_b32 s8, v247, 5
	v_ashrrev_i32_e32 v149, 31, v148
	v_ashrrev_i32_e32 v143, 31, v142
	v_readlane_b32 s9, v247, 6
	v_lshl_add_u64 v[144:145], v[148:149], 3, s[92:93]
	v_readlane_b32 s82, v246, 11
	v_lshl_add_u64 v[146:147], v[142:143], 1, s[8:9]
	global_load_dwordx2 v[142:143], v[144:145], off
	s_mov_b64 s[8:9], 0x100000
	v_readlane_b32 s83, v246, 12
	s_waitcnt vmcnt(0)
	v_ffbh_u32_e32 v153, v143
	v_min_u32_e32 v153, 32, v153
	v_lshlrev_b64 v[142:143], v153, v[142:143]
	v_min_u32_e32 v142, 1, v142
	v_or_b32_e32 v142, v143, v142
	v_cvt_f32_u32_e32 v142, v142
	v_sub_u32_e32 v143, 32, v153
	v_ldexp_f32 v142, v142, v143
	v_fmamk_f32 v142, v142, 0x2e000000, v211
	v_cmp_gt_f32_e32 vcc, s20, v142
	v_mul_f32_e32 v143, 0x4b800000, v142
	s_nop 0
	v_cndmask_b32_e32 v142, v142, v143, vcc
	v_rsq_f32_e32 v142, v142
	s_nop 0
	v_mul_f32_e32 v143, 0x45800000, v142
	v_cndmask_b32_e32 v154, v142, v143, vcc
	v_lshlrev_b64 v[142:143], 13, v[148:149]
	v_lshl_add_u64 v[142:143], v[146:147], 0, v[142:143]
	v_pk_mul_f32 v[128:129], v[128:129], v[154:155] op_sel_hi:[1,0]
	v_pk_mul_f32 v[126:127], v[126:127], v[154:155] op_sel_hi:[1,0]
	v_pk_mul_f32 v[156:157], v[124:125], v[154:155] op_sel_hi:[1,0]
	v_pk_mul_f32 v[124:125], v[122:123], v[154:155] op_sel_hi:[1,0]
	v_cvt_pk_bf16_f32 v122, v126, v127
	v_cvt_pk_bf16_f32 v123, v128, v129
	v_pk_mul_f32 v[118:119], v[118:119], v[154:155] op_sel_hi:[1,0]
	v_cvt_pk_bf16_f32 v124, v124, v125
	v_cvt_pk_bf16_f32 v125, v156, v157
	global_store_dwordx4 v[142:143], v[122:125], off sc1
	v_pk_mul_f32 v[120:121], v[120:121], v[154:155] op_sel_hi:[1,0]
	s_nop 0
	v_pk_mul_f32 v[122:123], v[116:117], v[154:155] op_sel_hi:[1,0]
	v_pk_mul_f32 v[116:117], v[114:115], v[154:155] op_sel_hi:[1,0]
	v_cvt_pk_bf16_f32 v114, v118, v119
	v_cvt_pk_bf16_f32 v115, v120, v121
	s_nop 0
	v_cvt_pk_bf16_f32 v116, v116, v117
	v_cvt_pk_bf16_f32 v117, v122, v123
	global_store_dwordx4 v[142:143], v[114:117], off offset:256 sc1
	s_nop 1
	v_or_b32_e32 v114, 16, v148
	v_ashrrev_i32_e32 v115, 31, v114
	v_lshl_add_u64 v[116:117], v[114:115], 3, s[92:93]
	global_load_dwordx2 v[116:117], v[116:117], off
	v_lshlrev_b64 v[114:115], 13, v[114:115]
	v_lshl_add_u64 v[114:115], v[146:147], 0, v[114:115]
	s_waitcnt vmcnt(0)
	v_ffbh_u32_e32 v118, v117
	v_min_u32_e32 v118, 32, v118
	v_lshlrev_b64 v[116:117], v118, v[116:117]
	v_min_u32_e32 v116, 1, v116
	v_or_b32_e32 v116, v117, v116
	v_cvt_f32_u32_e32 v116, v116
	v_sub_u32_e32 v117, 32, v118
	v_ldexp_f32 v116, v116, v117
	v_fmamk_f32 v116, v116, 0x2e000000, v211
	v_cmp_gt_f32_e32 vcc, s20, v116
	v_mul_f32_e32 v117, 0x4b800000, v116
	s_nop 0
	v_cndmask_b32_e32 v116, v116, v117, vcc
	v_rsq_f32_e32 v116, v116
	s_nop 0
	v_mul_f32_e32 v117, 0x45800000, v116
	v_cndmask_b32_e32 v116, v116, v117, vcc
	v_pk_mul_f32 v[112:113], v[112:113], v[116:117] op_sel_hi:[1,0]
	v_pk_mul_f32 v[110:111], v[110:111], v[116:117] op_sel_hi:[1,0]
	v_pk_mul_f32 v[118:119], v[108:109], v[116:117] op_sel_hi:[1,0]
	v_pk_mul_f32 v[108:109], v[106:107], v[116:117] op_sel_hi:[1,0]
	v_cvt_pk_bf16_f32 v106, v110, v111
	v_cvt_pk_bf16_f32 v107, v112, v113
	v_pk_mul_f32 v[102:103], v[102:103], v[116:117] op_sel_hi:[1,0]
	v_cvt_pk_bf16_f32 v108, v108, v109
	v_cvt_pk_bf16_f32 v109, v118, v119
	global_store_dwordx4 v[114:115], v[106:109], off sc1
	v_pk_mul_f32 v[104:105], v[104:105], v[116:117] op_sel_hi:[1,0]
	s_nop 0
	v_pk_mul_f32 v[106:107], v[100:101], v[116:117] op_sel_hi:[1,0]
	v_pk_mul_f32 v[100:101], v[98:99], v[116:117] op_sel_hi:[1,0]
	v_cvt_pk_bf16_f32 v98, v102, v103
	v_cvt_pk_bf16_f32 v99, v104, v105
	s_nop 0
	v_cvt_pk_bf16_f32 v100, v100, v101
	v_cvt_pk_bf16_f32 v101, v106, v107
	global_store_dwordx4 v[114:115], v[98:101], off offset:256 sc1
	s_nop 1
	v_or_b32_e32 v98, 32, v148
	v_ashrrev_i32_e32 v99, 31, v98
	v_lshl_add_u64 v[100:101], v[98:99], 3, s[92:93]
	global_load_dwordx2 v[100:101], v[100:101], off
	v_lshlrev_b64 v[98:99], 13, v[98:99]
	v_lshl_add_u64 v[98:99], v[146:147], 0, v[98:99]
	s_waitcnt vmcnt(0)
	v_ffbh_u32_e32 v102, v101
	v_min_u32_e32 v102, 32, v102
	v_lshlrev_b64 v[100:101], v102, v[100:101]
	v_min_u32_e32 v100, 1, v100
	v_or_b32_e32 v100, v101, v100
	v_cvt_f32_u32_e32 v100, v100
	v_sub_u32_e32 v101, 32, v102
	v_ldexp_f32 v100, v100, v101
	v_fmamk_f32 v100, v100, 0x2e000000, v211
	v_cmp_gt_f32_e32 vcc, s20, v100
	v_mul_f32_e32 v101, 0x4b800000, v100
	s_nop 0
	v_cndmask_b32_e32 v100, v100, v101, vcc
	v_rsq_f32_e32 v100, v100
	s_nop 0
	v_mul_f32_e32 v101, 0x45800000, v100
	v_cndmask_b32_e32 v100, v100, v101, vcc
	v_pk_mul_f32 v[96:97], v[96:97], v[100:101] op_sel_hi:[1,0]
	v_pk_mul_f32 v[94:95], v[94:95], v[100:101] op_sel_hi:[1,0]
	v_pk_mul_f32 v[102:103], v[92:93], v[100:101] op_sel_hi:[1,0]
	v_pk_mul_f32 v[92:93], v[90:91], v[100:101] op_sel_hi:[1,0]
	v_cvt_pk_bf16_f32 v90, v94, v95
	v_cvt_pk_bf16_f32 v91, v96, v97
	v_pk_mul_f32 v[86:87], v[86:87], v[100:101] op_sel_hi:[1,0]
	v_cvt_pk_bf16_f32 v92, v92, v93
	v_cvt_pk_bf16_f32 v93, v102, v103
	global_store_dwordx4 v[98:99], v[90:93], off sc1
	v_pk_mul_f32 v[88:89], v[88:89], v[100:101] op_sel_hi:[1,0]
	s_nop 0
	v_pk_mul_f32 v[90:91], v[84:85], v[100:101] op_sel_hi:[1,0]
	v_pk_mul_f32 v[84:85], v[82:83], v[100:101] op_sel_hi:[1,0]
	v_cvt_pk_bf16_f32 v82, v86, v87
	v_cvt_pk_bf16_f32 v83, v88, v89
	s_nop 0
	v_cvt_pk_bf16_f32 v84, v84, v85
	v_cvt_pk_bf16_f32 v85, v90, v91
	global_store_dwordx4 v[98:99], v[82:85], off offset:256 sc1
	s_nop 1
	v_or_b32_e32 v82, 48, v148
	v_ashrrev_i32_e32 v83, 31, v82
	v_lshl_add_u64 v[84:85], v[82:83], 3, s[92:93]
	global_load_dwordx2 v[84:85], v[84:85], off
	v_lshlrev_b64 v[82:83], 13, v[82:83]
	v_lshl_add_u64 v[82:83], v[146:147], 0, v[82:83]
	s_waitcnt vmcnt(0)
	v_ffbh_u32_e32 v86, v85
	v_min_u32_e32 v86, 32, v86
	v_lshlrev_b64 v[84:85], v86, v[84:85]
	v_min_u32_e32 v84, 1, v84
	v_or_b32_e32 v84, v85, v84
	v_cvt_f32_u32_e32 v84, v84
	v_sub_u32_e32 v85, 32, v86
	v_ldexp_f32 v84, v84, v85
	v_fmamk_f32 v84, v84, 0x2e000000, v211
	v_cmp_gt_f32_e32 vcc, s20, v84
	v_mul_f32_e32 v85, 0x4b800000, v84
	s_nop 0
	v_cndmask_b32_e32 v84, v84, v85, vcc
	v_rsq_f32_e32 v84, v84
	s_nop 0
	v_mul_f32_e32 v85, 0x45800000, v84
	v_cndmask_b32_e32 v84, v84, v85, vcc
	v_pk_mul_f32 v[80:81], v[80:81], v[84:85] op_sel_hi:[1,0]
	v_pk_mul_f32 v[78:79], v[78:79], v[84:85] op_sel_hi:[1,0]
	v_pk_mul_f32 v[86:87], v[76:77], v[84:85] op_sel_hi:[1,0]
	v_pk_mul_f32 v[76:77], v[74:75], v[84:85] op_sel_hi:[1,0]
	v_cvt_pk_bf16_f32 v74, v78, v79
	v_cvt_pk_bf16_f32 v75, v80, v81
	v_pk_mul_f32 v[72:73], v[72:73], v[84:85] op_sel_hi:[1,0]
	v_cvt_pk_bf16_f32 v76, v76, v77
	v_cvt_pk_bf16_f32 v77, v86, v87
	global_store_dwordx4 v[82:83], v[74:77], off sc1
	v_pk_mul_f32 v[70:71], v[70:71], v[84:85] op_sel_hi:[1,0]
	s_nop 0
	v_pk_mul_f32 v[74:75], v[68:69], v[84:85] op_sel_hi:[1,0]
	v_pk_mul_f32 v[68:69], v[66:67], v[84:85] op_sel_hi:[1,0]
	v_cvt_pk_bf16_f32 v66, v70, v71
	v_cvt_pk_bf16_f32 v67, v72, v73
	s_nop 0
	v_cvt_pk_bf16_f32 v68, v68, v69
	v_cvt_pk_bf16_f32 v69, v74, v75
	global_store_dwordx4 v[82:83], v[66:69], off offset:256 sc1
	global_load_dwordx2 v[66:67], v[144:145], off offset:1024
	s_waitcnt vmcnt(0)
	v_ffbh_u32_e32 v68, v67
	v_min_u32_e32 v68, 32, v68
	v_lshlrev_b64 v[66:67], v68, v[66:67]
	v_min_u32_e32 v66, 1, v66
	v_or_b32_e32 v66, v67, v66
	v_cvt_f32_u32_e32 v66, v66
	v_sub_u32_e32 v67, 32, v68
	v_lshl_add_u64 v[68:69], v[142:143], 0, s[8:9]
	s_mov_b32 s8, 0x100000
	v_ldexp_f32 v66, v66, v67
	v_fmamk_f32 v66, v66, 0x2e000000, v211
	v_cmp_gt_f32_e32 vcc, s20, v66
	v_mul_f32_e32 v67, 0x4b800000, v66
	s_nop 0
	v_cndmask_b32_e32 v66, v66, v67, vcc
	v_rsq_f32_e32 v66, v66
	s_nop 0
	v_mul_f32_e32 v67, 0x45800000, v66
	v_cndmask_b32_e32 v66, v66, v67, vcc
	v_pk_mul_f32 v[62:63], v[62:63], v[66:67] op_sel_hi:[1,0]
	v_pk_mul_f32 v[70:71], v[60:61], v[66:67] op_sel_hi:[1,0]
	v_pk_mul_f32 v[60:61], v[58:59], v[66:67] op_sel_hi:[1,0]
	v_cvt_pk_bf16_f32 v58, v62, v63
	v_add_co_u32_e32 v62, vcc, s8, v142
	v_pk_mul_f32 v[64:65], v[64:65], v[66:67] op_sel_hi:[1,0]
	s_nop 0
	v_addc_co_u32_e32 v63, vcc, 0, v143, vcc
	v_cvt_pk_bf16_f32 v59, v64, v65
	v_cvt_pk_bf16_f32 v60, v60, v61
	v_cvt_pk_bf16_f32 v61, v70, v71
	global_store_dwordx4 v[62:63], v[58:61], off sc1
	v_pk_mul_f32 v[56:57], v[56:57], v[66:67] op_sel_hi:[1,0]
	v_pk_mul_f32 v[54:55], v[54:55], v[66:67] op_sel_hi:[1,0]
	v_pk_mul_f32 v[58:59], v[52:53], v[66:67] op_sel_hi:[1,0]
	v_pk_mul_f32 v[52:53], v[50:51], v[66:67] op_sel_hi:[1,0]
	v_cvt_pk_bf16_f32 v50, v54, v55
	v_cvt_pk_bf16_f32 v51, v56, v57
	s_mov_b64 s[8:9], 0x120000
	v_cvt_pk_bf16_f32 v52, v52, v53
	v_cvt_pk_bf16_f32 v53, v58, v59
	global_store_dwordx4 v[68:69], v[50:53], off offset:256 sc1
	global_load_dwordx2 v[50:51], v[144:145], off offset:1152
	s_waitcnt vmcnt(0)
	v_ffbh_u32_e32 v52, v51
	v_min_u32_e32 v52, 32, v52
	v_lshlrev_b64 v[50:51], v52, v[50:51]
	v_min_u32_e32 v50, 1, v50
	v_or_b32_e32 v50, v51, v50
	v_cvt_f32_u32_e32 v50, v50
	v_sub_u32_e32 v51, 32, v52
	v_lshl_add_u64 v[52:53], v[142:143], 0, s[8:9]
	s_mov_b32 s8, 0x120000
	v_ldexp_f32 v50, v50, v51
	v_fmamk_f32 v50, v50, 0x2e000000, v211
	v_cmp_gt_f32_e32 vcc, s20, v50
	v_mul_f32_e32 v51, 0x4b800000, v50
	s_nop 0
	v_cndmask_b32_e32 v50, v50, v51, vcc
	v_rsq_f32_e32 v50, v50
	s_nop 0
	v_mul_f32_e32 v51, 0x45800000, v50
	v_cndmask_b32_e32 v50, v50, v51, vcc
	v_pk_mul_f32 v[46:47], v[46:47], v[50:51] op_sel_hi:[1,0]
	v_pk_mul_f32 v[54:55], v[44:45], v[50:51] op_sel_hi:[1,0]
	v_pk_mul_f32 v[44:45], v[42:43], v[50:51] op_sel_hi:[1,0]
	v_cvt_pk_bf16_f32 v42, v46, v47
	v_add_co_u32_e32 v46, vcc, s8, v142
	v_pk_mul_f32 v[48:49], v[48:49], v[50:51] op_sel_hi:[1,0]
	s_nop 0
	v_addc_co_u32_e32 v47, vcc, 0, v143, vcc
	v_cvt_pk_bf16_f32 v43, v48, v49
	v_cvt_pk_bf16_f32 v44, v44, v45
	v_cvt_pk_bf16_f32 v45, v54, v55
	global_store_dwordx4 v[46:47], v[42:45], off sc1
	v_pk_mul_f32 v[40:41], v[40:41], v[50:51] op_sel_hi:[1,0]
	v_pk_mul_f32 v[38:39], v[38:39], v[50:51] op_sel_hi:[1,0]
	v_pk_mul_f32 v[42:43], v[36:37], v[50:51] op_sel_hi:[1,0]
	v_pk_mul_f32 v[36:37], v[34:35], v[50:51] op_sel_hi:[1,0]
	v_cvt_pk_bf16_f32 v34, v38, v39
	v_cvt_pk_bf16_f32 v35, v40, v41
	s_mov_b64 s[8:9], 0x140000
	v_cvt_pk_bf16_f32 v36, v36, v37
	v_cvt_pk_bf16_f32 v37, v42, v43
	global_store_dwordx4 v[52:53], v[34:37], off offset:256 sc1
	global_load_dwordx2 v[34:35], v[144:145], off offset:1280
	s_waitcnt vmcnt(0)
	v_ffbh_u32_e32 v36, v35
	v_min_u32_e32 v36, 32, v36
	v_lshlrev_b64 v[34:35], v36, v[34:35]
	v_min_u32_e32 v34, 1, v34
	v_or_b32_e32 v34, v35, v34
	v_cvt_f32_u32_e32 v34, v34
	v_sub_u32_e32 v35, 32, v36
	v_lshl_add_u64 v[36:37], v[142:143], 0, s[8:9]
	s_mov_b32 s8, 0x140000
	v_ldexp_f32 v34, v34, v35
	v_fmamk_f32 v34, v34, 0x2e000000, v211
	v_cmp_gt_f32_e32 vcc, s20, v34
	v_mul_f32_e32 v35, 0x4b800000, v34
	s_nop 0
	v_cndmask_b32_e32 v34, v34, v35, vcc
	v_rsq_f32_e32 v34, v34
	s_nop 0
	v_mul_f32_e32 v35, 0x45800000, v34
	v_cndmask_b32_e32 v34, v34, v35, vcc
	v_pk_mul_f32 v[30:31], v[30:31], v[34:35] op_sel_hi:[1,0]
	v_pk_mul_f32 v[38:39], v[28:29], v[34:35] op_sel_hi:[1,0]
	v_pk_mul_f32 v[28:29], v[26:27], v[34:35] op_sel_hi:[1,0]
	v_cvt_pk_bf16_f32 v26, v30, v31
	v_add_co_u32_e32 v30, vcc, s8, v142
	v_pk_mul_f32 v[32:33], v[32:33], v[34:35] op_sel_hi:[1,0]
	s_nop 0
	v_addc_co_u32_e32 v31, vcc, 0, v143, vcc
	v_cvt_pk_bf16_f32 v27, v32, v33
	v_cvt_pk_bf16_f32 v28, v28, v29
	v_cvt_pk_bf16_f32 v29, v38, v39
	global_store_dwordx4 v[30:31], v[26:29], off sc1
	v_pk_mul_f32 v[24:25], v[24:25], v[34:35] op_sel_hi:[1,0]
	v_pk_mul_f32 v[22:23], v[22:23], v[34:35] op_sel_hi:[1,0]
	v_pk_mul_f32 v[26:27], v[20:21], v[34:35] op_sel_hi:[1,0]
	v_pk_mul_f32 v[20:21], v[18:19], v[34:35] op_sel_hi:[1,0]
	v_cvt_pk_bf16_f32 v18, v22, v23
	v_cvt_pk_bf16_f32 v19, v24, v25
	s_mov_b64 s[8:9], 0x160000
	v_cvt_pk_bf16_f32 v20, v20, v21
	v_cvt_pk_bf16_f32 v21, v26, v27
	global_store_dwordx4 v[36:37], v[18:21], off offset:256 sc1
	global_load_dwordx2 v[18:19], v[144:145], off offset:1408
	s_waitcnt vmcnt(0)
	v_ffbh_u32_e32 v20, v19
	v_min_u32_e32 v20, 32, v20
	v_lshlrev_b64 v[18:19], v20, v[18:19]
	v_min_u32_e32 v18, 1, v18
	v_or_b32_e32 v18, v19, v18
	v_cvt_f32_u32_e32 v18, v18
	v_sub_u32_e32 v19, 32, v20
	v_lshl_add_u64 v[20:21], v[142:143], 0, s[8:9]
	s_mov_b32 s8, 0x160000
	v_ldexp_f32 v18, v18, v19
	v_fmamk_f32 v18, v18, 0x2e000000, v211
	v_cmp_gt_f32_e32 vcc, s20, v18
	v_mul_f32_e32 v19, 0x4b800000, v18
	s_nop 0
	v_cndmask_b32_e32 v18, v18, v19, vcc
	v_rsq_f32_e32 v18, v18
	s_nop 0
	v_mul_f32_e32 v19, 0x45800000, v18
	v_cndmask_b32_e32 v18, v18, v19, vcc
	v_pk_mul_f32 v[14:15], v[14:15], v[18:19] op_sel_hi:[1,0]
	v_pk_mul_f32 v[22:23], v[12:13], v[18:19] op_sel_hi:[1,0]
	v_pk_mul_f32 v[12:13], v[10:11], v[18:19] op_sel_hi:[1,0]
	v_cvt_pk_bf16_f32 v10, v14, v15
	v_add_co_u32_e32 v14, vcc, s8, v142
	v_pk_mul_f32 v[16:17], v[16:17], v[18:19] op_sel_hi:[1,0]
	s_nop 0
	v_addc_co_u32_e32 v15, vcc, 0, v143, vcc
	v_cvt_pk_bf16_f32 v11, v16, v17
	v_cvt_pk_bf16_f32 v12, v12, v13
	v_cvt_pk_bf16_f32 v13, v22, v23
	global_store_dwordx4 v[14:15], v[10:13], off sc1
	s_mov_b64 s[8:9], -1
	s_andn2_b64 vcc, exec, s[44:45]
	v_pk_mul_f32 v[10:11], v[4:5], v[18:19] op_sel_hi:[1,0]
	v_pk_mul_f32 v[4:5], v[2:3], v[18:19] op_sel_hi:[1,0]
	v_pk_mul_f32 v[8:9], v[8:9], v[18:19] op_sel_hi:[1,0]
	v_pk_mul_f32 v[6:7], v[6:7], v[18:19] op_sel_hi:[1,0]
	s_nop 0
	v_cvt_pk_bf16_f32 v2, v6, v7
	v_cvt_pk_bf16_f32 v3, v8, v9
	v_cvt_pk_bf16_f32 v4, v4, v5
	v_cvt_pk_bf16_f32 v5, v10, v11
	global_store_dwordx4 v[20:21], v[2:5], off offset:256 sc1
	s_cbranch_vccnz .LBB0_709
	s_andn2_b64 vcc, exec, s[0:1]
	s_cbranch_vccnz .LBB0_708
	s_barrier
	s_branch .LBB0_708
